# ssd_out phase tile loop: A_log load issued together with the dt / dt_bias loads (same change as in the states tile)
# baseline (speedup 1.0000x reference)
.LBB0_1695:
	v_mov_b32_e32 v134, v252
	s_barrier
	s_load_dwordx2 s[54:55], s[0:1], 0xd0
	v_and_b32_e32 v135, 63, v134
	s_lshl_b32 s15, s52, 6
	v_readfirstlane_b32 s16, v134
	v_or_b32_e32 v0, s15, v135
	s_ashr_i32 s58, s16, 6
	v_ashrrev_i32_e32 v1, 31, v0
	s_ashr_i32 s59, s58, 31
	v_lshlrev_b64 v[0:1], 5, v[0:1]
	s_waitcnt lgkmcnt(0)
	v_lshl_add_u64 v[0:1], s[54:55], 0, v[0:1]
	s_lshl_b64 s[36:37], s[58:59], 2
	v_lshl_add_u64 v[0:1], v[0:1], 0, s[36:37]
	s_mov_b32 s2, 0x22e0000
	v_add_co_u32_e32 v0, vcc, s2, v0
	s_load_dwordx2 s[2:3], s[0:1], 0x60
	s_load_dwordx2 s[98:99], s[0:1], 0x68
	s_nop 0
	v_addc_co_u32_e32 v1, vcc, 0, v1, vcc
	global_load_dword v0, v[0:1], off
	s_waitcnt lgkmcnt(0)
	s_add_u32 s2, s2, s36
	s_addc_u32 s3, s3, s37
	global_load_dword v1, v137, s[2:3]
	s_add_u32 s98, s98, s36
	s_addc_u32 s99, s99, s37
	global_load_dword v250, v137, s[98:99]
	s_mov_b32 s2, 0x41a00000
	s_waitcnt vmcnt(0)
	v_add_f32_e32 v0, v0, v1
	v_cmp_nlt_f32_e32 vcc, s2, v0
	s_and_saveexec_b64 s[2:3], vcc
	s_cbranch_execz .LBB0_1697
	v_mul_f32_e32 v1, 0x3fb8aa3b, v0
	v_rndne_f32_e32 v2, v1
	v_sub_f32_e32 v3, v1, v2
	v_fma_f32 v1, v0, s8, -v1
	v_fmac_f32_e32 v1, 0x32a5705f, v0
	v_add_f32_e32 v1, v3, v1
	v_cvt_i32_f32_e32 v2, v2
	v_exp_f32_e32 v1, v1
	v_cmp_ngt_f32_e32 vcc, s9, v0
	s_mov_b32 s4, 0x3f2aaaab
	v_ldexp_f32 v1, v1, v2
	v_cndmask_b32_e32 v1, 0, v1, vcc
	v_cmp_nlt_f32_e32 vcc, s10, v0
	s_nop 1
	v_cndmask_b32_e32 v14, v183, v1, vcc
	v_add_f32_e32 v2, 1.0, v14
	v_add_f32_e32 v0, -1.0, v2
	v_sub_f32_e32 v1, v0, v2
	v_add_f32_e32 v1, 1.0, v1
	v_sub_f32_e32 v0, v14, v0
	v_add_f32_e32 v3, v0, v1
	v_frexp_mant_f32_e32 v4, v2
	v_cvt_f64_f32_e32 v[0:1], v2
	v_frexp_exp_i32_f64_e32 v0, v[0:1]
	v_cmp_gt_f32_e32 vcc, s4, v4
	s_mov_b32 s4, 0x3f317218
	s_nop 0
	v_subbrev_co_u32_e32 v8, vcc, 0, v0, vcc
	v_sub_u32_e32 v0, 0, v8
	v_ldexp_f32 v1, v2, v0
	v_add_f32_e32 v2, -1.0, v1
	v_add_f32_e32 v4, 1.0, v1
	v_ldexp_f32 v0, v3, v0
	v_add_f32_e32 v3, 1.0, v2
	v_add_f32_e32 v5, -1.0, v4
	v_sub_f32_e32 v3, v1, v3
	v_sub_f32_e32 v1, v1, v5
	v_add_f32_e32 v3, v0, v3
	v_add_f32_e32 v0, v0, v1
	v_add_f32_e32 v9, v4, v0
	v_rcp_f32_e32 v11, v9
	v_sub_f32_e32 v1, v4, v9
	v_add_f32_e32 v10, v0, v1
	v_add_f32_e32 v1, v2, v3
	v_mul_f32_e32 v13, v1, v11
	v_sub_f32_e32 v0, v2, v1
	v_mul_f32_e32 v2, v9, v13
	v_fma_f32 v4, v13, v9, -v2
	v_fmac_f32_e32 v4, v13, v10
	v_add_f32_e32 v12, v3, v0
	v_add_f32_e32 v0, v2, v4
	v_sub_f32_e32 v3, v1, v0
	v_pk_add_f32 v[6:7], v[0:1], v[2:3] neg_lo:[0,1] neg_hi:[0,1]
	v_mov_b32_e32 v5, v0
	v_pk_add_f32 v[0:1], v[6:7], v[4:5] neg_lo:[0,1] neg_hi:[0,1]
	s_nop 0
	v_add_f32_e32 v1, v12, v1
	v_add_f32_e32 v0, v0, v1
	v_add_f32_e32 v1, v3, v0
	v_mul_f32_e32 v12, v11, v1
	v_mul_f32_e32 v2, v9, v12
	v_fma_f32 v4, v12, v9, -v2
	v_fmac_f32_e32 v4, v12, v10
	v_sub_f32_e32 v3, v3, v1
	v_add_f32_e32 v9, v0, v3
	v_add_f32_e32 v0, v2, v4
	v_sub_f32_e32 v3, v1, v0
	v_pk_add_f32 v[6:7], v[0:1], v[2:3] neg_lo:[0,1] neg_hi:[0,1]
	v_mov_b32_e32 v5, v0
	v_pk_add_f32 v[0:1], v[6:7], v[4:5] neg_lo:[0,1] neg_hi:[0,1]
	s_nop 0
	v_add_f32_e32 v1, v9, v1
	v_add_f32_e32 v0, v0, v1
	v_add_f32_e32 v1, v13, v12
	v_add_f32_e32 v0, v3, v0
	v_sub_f32_e32 v2, v1, v13
	v_mul_f32_e32 v0, v11, v0
	v_sub_f32_e32 v2, v12, v2
	v_add_f32_e32 v2, v2, v0
	v_add_f32_e32 v4, v1, v2
	v_mul_f32_e32 v5, v4, v4
	v_fmamk_f32 v0, v5, 0x3e9b6dac, v180
	v_fmaak_f32 v139, v5, v0, 0x3f2aaada
	v_cvt_f32_i32_e32 v0, v8
	v_sub_f32_e32 v1, v4, v1
	v_sub_f32_e32 v1, v2, v1
	v_ldexp_f32 v6, v1, 1
	v_mul_f32_e32 v1, v4, v5
	v_ldexp_f32 v3, v4, 1
	v_pk_mul_f32 v[4:5], v[0:1], v[138:139]
	s_nop 0
	v_fma_f32 v2, v0, s4, -v4
	v_fmac_f32_e32 v2, 0xb102e308, v0
	v_pk_add_f32 v[0:1], v[4:5], v[2:3]
	s_mov_b32 s4, 0x7f800000
	v_sub_f32_e32 v3, v1, v3
	v_sub_f32_e32 v3, v5, v3
	v_add_f32_e32 v7, v6, v3
	v_mov_b32_e32 v6, v4
	v_pk_add_f32 v[4:5], v[0:1], v[4:5] neg_lo:[0,1] neg_hi:[0,1]
	v_pk_add_f32 v[8:9], v[0:1], v[6:7]
	v_mov_b32_e32 v3, v0
	v_mov_b32_e32 v5, v9
	v_pk_add_f32 v[10:11], v[2:3], v[4:5] neg_lo:[0,1] neg_hi:[0,1]
	v_pk_add_f32 v[2:3], v[2:3], v[4:5]
	v_mov_b32_e32 v6, v7
	v_pk_add_f32 v[4:5], v[2:3], v[0:1] op_sel:[1,0] op_sel_hi:[0,1] neg_lo:[0,1] neg_hi:[0,1]
	v_pk_add_f32 v[12:13], v[8:9], v[4:5] op_sel_hi:[1,0] neg_lo:[0,1] neg_hi:[0,1]
	v_mov_b32_e32 v8, v9
	v_mov_b32_e32 v9, v3
	v_pk_mov_b32 v[4:5], v[0:1], v[4:5] op_sel:[1,0]
	v_mov_b32_e32 v7, v0
	v_pk_add_f32 v[4:5], v[8:9], v[4:5] neg_lo:[0,1] neg_hi:[0,1]
	v_mov_b32_e32 v12, v10
	v_pk_add_f32 v[0:1], v[6:7], v[4:5] neg_lo:[0,1] neg_hi:[0,1]
	v_mov_b32_e32 v11, v3
	v_pk_add_f32 v[4:5], v[12:13], v[0:1]
	v_cmp_neq_f32_e32 vcc, s4, v14
	v_pk_add_f32 v[6:7], v[4:5], v[4:5] op_sel:[0,1] op_sel_hi:[1,0]
	s_mov_b32 s4, 0x33800000
	v_pk_add_f32 v[2:3], v[2:3], v[6:7] op_sel:[1,0] op_sel_hi:[0,1]
	v_mov_b32_e32 v5, v2
	v_pk_add_f32 v[8:9], v[4:5], v[10:11] neg_lo:[0,1] neg_hi:[0,1]
	v_mov_b32_e32 v1, v6
	v_sub_f32_e32 v3, v4, v8
	v_pk_add_f32 v[0:1], v[0:1], v[8:9] neg_lo:[0,1] neg_hi:[0,1]
	v_sub_f32_e32 v3, v10, v3
	v_add_f32_e32 v0, v0, v3
	v_add_f32_e32 v0, v0, v1
	v_add_f32_e32 v0, v2, v0
	v_cndmask_b32_e32 v0, v183, v0, vcc
	v_cmp_lt_f32_e64 vcc, |v14|, s4
	s_nop 1
	v_cndmask_b32_e32 v0, v0, v14, vcc
.LBB0_1697:
	s_or_b64 exec, exec, s[2:3]
	s_load_dwordx2 s[4:5], s[0:1], 0x68
	s_load_dwordx4 s[44:47], s[0:1], 0x50
	s_and_b32 s2, s52, 0x7f
	s_cmp_lg_u32 s2, 0
	s_cselect_b64 s[2:3], -1, 0
	s_waitcnt lgkmcnt(0)
	s_add_u32 s4, s4, s36
	s_addc_u32 s5, s5, s37
	v_mov_b32_e32 v1, v250
	v_and_b32_e32 v139, 64, v184
	v_add_u32_e32 v2, -1, v184
	v_add_u32_e32 v3, -2, v184
	v_cmp_lt_i32_e32 vcc, v2, v139
	v_add_u32_e32 v4, -4, v184
	v_add_u32_e32 v5, -8, v184
	v_cndmask_b32_e32 v2, v2, v184, vcc
	v_cmp_lt_i32_e32 vcc, v3, v139
	v_lshlrev_b32_e32 v2, 2, v2
	v_add_u32_e32 v6, -16, v184
	v_cndmask_b32_e32 v3, v3, v184, vcc
	v_cmp_lt_i32_e32 vcc, v4, v139
	v_subrev_u32_e32 v7, 32, v184
	v_lshlrev_b32_e32 v3, 2, v3
	v_cndmask_b32_e32 v4, v4, v184, vcc
	v_cmp_lt_i32_e32 vcc, v5, v139
	v_cmp_gt_u32_e64 s[42:43], 8, v135
	v_and_b32_e32 v120, 0x7f, v134
	v_cndmask_b32_e32 v5, v5, v184, vcc
	v_lshlrev_b32_e32 v136, 5, v120
	s_mov_b64 s[4:5], 0x1000
	s_and_b32 s56, s16, 0xffffffc0
	v_or_b32_e32 v14, s56, v135
	v_ashrrev_i32_e32 v40, 3, v134
	s_waitcnt vmcnt(0)
	v_mul_f32_e32 v8, 0x3fb8aa3b, v1
	v_fma_f32 v9, v1, s8, -v8
	v_rndne_f32_e32 v10, v8
	v_fmac_f32_e32 v9, 0x32a5705f, v1
	v_sub_f32_e32 v8, v8, v10
	v_add_f32_e32 v8, v8, v9
	v_cvt_i32_f32_e32 v10, v10
	v_exp_f32_e32 v8, v8
	v_cmp_ngt_f32_e32 vcc, s9, v1
	v_ldexp_f32 v8, v8, v10
	s_nop 0
	v_cndmask_b32_e32 v8, 0, v8, vcc
	v_cmp_nlt_f32_e32 vcc, s10, v1
	s_nop 1
	v_cndmask_b32_e32 v1, v183, v8, vcc
	v_mul_f32_e64 v8, v0, -v1
	ds_bpermute_b32 v2, v2, v8
	v_cmp_lt_i32_e32 vcc, v6, v139
	s_waitcnt lgkmcnt(0)
	v_fma_f32 v1, v0, -v1, v2
	v_cndmask_b32_e32 v6, v6, v184, vcc
	v_cmp_lt_i32_e32 vcc, v7, v139
	v_lshlrev_b32_e32 v12, 2, v6
	s_nop 0
	v_cndmask_b32_e32 v7, v7, v184, vcc
	v_cmp_eq_u32_e32 vcc, 0, v135
	v_lshlrev_b32_e32 v13, 2, v7
	s_nop 0
	v_cndmask_b32_e32 v1, v1, v8, vcc
	ds_bpermute_b32 v2, v3, v1
	v_cmp_gt_u32_e32 vcc, 2, v135
	v_lshlrev_b32_e32 v3, 2, v4
	v_lshlrev_b32_e32 v8, 2, v5
	s_waitcnt lgkmcnt(0)
	v_add_f32_e32 v2, v1, v2
	v_cndmask_b32_e32 v1, v2, v1, vcc
	ds_bpermute_b32 v6, v3, v1
	v_cmp_gt_u32_e32 vcc, 4, v135
	v_lshl_add_u64 v[2:3], s[44:45], 0, v[136:137]
	v_lshl_add_u64 v[4:5], v[2:3], 0, s[4:5]
	s_movk_i32 s4, 0x2000
	s_waitcnt lgkmcnt(0)
	v_add_f32_e32 v6, v1, v6
	v_cndmask_b32_e32 v1, v6, v1, vcc
	ds_bpermute_b32 v7, v8, v1
	v_add_co_u32_e32 v6, vcc, s4, v2
	s_mov_b64 s[4:5], 0x2000
	v_lshl_add_u64 v[8:9], v[2:3], 0, s[4:5]
	s_waitcnt lgkmcnt(0)
	v_add_f32_e32 v7, v1, v7
	v_cndmask_b32_e64 v1, v7, v1, s[42:43]
	ds_bpermute_b32 v15, v12, v1
	s_mov_b64 s[4:5], 0x3000
	v_addc_co_u32_e32 v7, vcc, 0, v3, vcc
	v_lshl_add_u64 v[10:11], v[2:3], 0, s[4:5]
	v_add_co_u32_e32 v12, vcc, 0x3000, v2
	v_lshl_add_u32 v2, v14, 2, 0
	s_waitcnt lgkmcnt(0)
	v_add_f32_e32 v14, v1, v15
	v_cmp_gt_u32_e64 s[42:43], 16, v135
	s_mov_b64 s[4:5], 0
	s_nop 0
	v_cndmask_b32_e64 v1, v14, v1, s[42:43]
	ds_bpermute_b32 v14, v13, v1
	v_addc_co_u32_e32 v13, vcc, 0, v3, vcc
	v_add_u32_e32 v3, 0x20800, v2
	ds_write_b32 v3, v0
	s_waitcnt lgkmcnt(1)
	v_add_f32_e32 v0, v1, v14
	v_cmp_gt_u32_e64 s[42:43], 32, v135
	v_add_u32_e32 v2, 0x21000, v2
	v_cmp_gt_i32_e32 vcc, 16, v40
	v_cndmask_b32_e64 v0, v0, v1, s[42:43]
	ds_write_b32 v2, v0
	s_waitcnt lgkmcnt(0)
	s_barrier
	global_load_dwordx4 v[24:27], v[6:7], off offset:-4096
	global_load_dwordx4 v[20:23], v[6:7], off
	global_load_dwordx4 v[0:3], v[4:5], off offset:16
	s_nop 0
	global_load_dwordx4 v[4:7], v[8:9], off offset:16
	global_load_dwordx4 v[28:31], v[12:13], off
	s_nop 0
	global_load_dwordx4 v[8:11], v[10:11], off offset:16
	s_nop 0
	global_load_dwordx4 v[12:15], v136, s[44:45] offset:16
	global_load_dwordx4 v[16:19], v136, s[46:47] offset:16
	global_load_dwordx4 v[32:35], v136, s[44:45]
	global_load_dwordx4 v[36:39], v136, s[46:47]
	s_and_saveexec_b64 s[6:7], vcc
	s_xor_b64 s[6:7], exec, s[6:7]
	s_and_b64 s[4:5], s[2:3], exec
	s_or_saveexec_b64 s[6:7], s[6:7]
	v_and_b32_e32 v121, -16, v40
	s_xor_b64 exec, exec, s[6:7]
	s_movk_i32 s17, 0x43
	v_cmp_gt_i32_e64 s[44:45], s17, v121
	s_andn2_b64 s[4:5], s[4:5], exec
	s_and_b64 s[18:19], s[44:45], exec
	s_or_b64 s[4:5], s[4:5], s[18:19]
	s_or_b64 exec, exec, s[6:7]
	v_lshlrev_b32_e32 v136, 4, v120
	v_lshl_add_u64 v[42:43], s[54:55], 0, v[136:137]
	s_mov_b64 s[6:7], 0xf77e200
	v_lshl_add_u64 v[116:117], v[42:43], 0, s[6:7]
	v_mov_b32_e32 v100, 0
	v_mov_b32_e32 v101, 0
	v_mov_b32_e32 v102, 0
	v_mov_b32_e32 v103, 0
	s_and_saveexec_b64 s[6:7], s[4:5]
	s_cbranch_execz .LBB0_1703
	v_add3_u32 v42, s15, -3, v121
	v_ashrrev_i32_e32 v43, 31, v42
	v_lshlrev_b64 v[42:43], 11, v[42:43]
	v_lshl_add_u64 v[42:43], v[116:117], 0, v[42:43]
	global_load_dwordx4 v[100:103], v[42:43], off
